# xcd barrier, non-leader workgroups: L1 invalidate issued before polling the XCD release word instead of after (on v37)
# speedup vs baseline: 1.0024x; 1.0023x over previous
; __device__ __forceinline__ unsigned xb_ld(unsigned* p)              { return __hip_atomic_load(p, __ATOMIC_RELAXED, __HIP_MEMORY_SCOPE_AGENT); }
; __device__ __forceinline__ unsigned xb_add(unsigned* p, unsigned v) { return __hip_atomic_fetch_add(p, v, __ATOMIC_RELAXED, __HIP_MEMORY_SCOPE_AGENT); }
; #define XB_SPIN(cond, bar) do { unsigned _sp = 0; while (cond) { __builtin_amdgcn_s_sleep(1); \
;     if ((++_sp & 255u) == 0u) { if (xb_ld(&(bar)[XB_TMO])) break; if (_sp > XB_SPIN_CAP) { atomicAdd(&(bar)[XB_TMO], 1u); break; } } } } while (0)
; __device__ __forceinline__ void xcd_barrier(const XcdBarrier& b) {
;     ...
;         const unsigned old = xb_add(&bar[XB_XSUB(b.x)], 1u);
;         const unsigned gen = old / nloc;
;         if (old + 1u == (gen + 1u) * nloc) {
;             __builtin_amdgcn_fence(__ATOMIC_RELEASE, "agent");
;             asm volatile("s_waitcnt vmcnt(0)" ::: "memory");
;             const unsigned og = xb_add(&bar[XB_TOP], 1u);
;             const unsigned tg = og / nx;
;             if (og + 1u == (tg + 1u) * nx) xb_add(&bar[XB_TOPGEN], 1u);
;             else XB_SPIN(xb_ld(&bar[XB_TOPGEN]) == tg, bar);
;             __builtin_amdgcn_fence(__ATOMIC_ACQUIRE, "agent");
;             xb_add(&bar[XB_XGEN(b.x)], 1u);
;             asm volatile("s_waitcnt vmcnt(0)" ::: "memory");
;         } else {
;             XB_SPIN(xb_ld(&bar[XB_XGEN(b.x)]) == gen, bar);
.LBB0_159:
	v_readlane_b32 s0, v253, 48
	v_readlane_b32 s1, v253, 49
	v_cvt_f32_u32_e32 v2, v3
	v_sub_u32_e32 v5, 0, v3
	v_rcp_iflag_f32_e32 v2, v2
	s_nop 1
	global_atomic_add v4, v0, v217, s[0:1] sc0
	v_mul_f32_e32 v2, 0x4f7ffffe, v2
	v_cvt_u32_f32_e32 v2, v2
	v_mul_lo_u32 v5, v5, v2
	v_mul_hi_u32 v5, v2, v5
	v_add_u32_e32 v2, v2, v5
	s_waitcnt vmcnt(0)
	v_mul_hi_u32 v2, v4, v2
	v_mul_lo_u32 v5, v2, v3
	v_sub_u32_e32 v5, v4, v5
	v_add_u32_e32 v6, 1, v2
	v_sub_u32_e32 v7, v5, v3
	v_cmp_ge_u32_e32 vcc, v5, v3
	v_add_u32_e32 v4, 1, v4
	s_nop 0
	v_cndmask_b32_e32 v2, v2, v6, vcc
	v_cndmask_b32_e32 v5, v5, v7, vcc
	v_add_u32_e32 v6, 1, v2
	v_cmp_ge_u32_e32 vcc, v5, v3
	s_nop 1
	v_cndmask_b32_e32 v2, v2, v6, vcc
	v_mul_lo_u32 v5, v3, v2
	v_add_u32_e32 v3, v5, v3
	v_cmp_ne_u32_e32 vcc, v4, v3
	s_and_saveexec_b64 s[0:1], vcc
	s_xor_b64 s[0:1], exec, s[0:1]
	s_cbranch_execz .LBB0_173
	v_readlane_b32 s8, v253, 50
	v_readlane_b32 s9, v253, 51
	s_waitcnt lgkmcnt(0)
	s_nop 3
	buffer_inv sc1
	global_load_dword v1, v0, s[8:9] sc1
	s_waitcnt vmcnt(0)
	v_cmp_eq_u32_e32 vcc, v1, v2
	s_and_saveexec_b64 s[8:9], vcc
	s_cbranch_execz .LBB0_172
	s_mov_b32 s3, 1
	s_mov_b64 s[14:15], 0
	s_branch .LBB0_163

; __device__ __forceinline__ unsigned xb_ld(unsigned* p)              { return __hip_atomic_load(p, __ATOMIC_RELAXED, __HIP_MEMORY_SCOPE_AGENT); }
; #define XB_SPIN(cond, bar) do { unsigned _sp = 0; while (cond) { __builtin_amdgcn_s_sleep(1); \
;     if ((++_sp & 255u) == 0u) { if (xb_ld(&(bar)[XB_TMO])) break; if (_sp > XB_SPIN_CAP) { atomicAdd(&(bar)[XB_TMO], 1u); break; } } } } while (0)
; __device__ __forceinline__ void xcd_barrier(const XcdBarrier& b) {
;     ...
;             XB_SPIN(xb_ld(&bar[XB_XGEN(b.x)]) == gen, bar);
;             __builtin_amdgcn_fence(__ATOMIC_ACQUIRE, "agent");
;             asm volatile("s_waitcnt vmcnt(0)" ::: "memory");
.LBB0_172:
	s_or_b64 exec, exec, s[8:9]
	s_waitcnt vmcnt(0)
	s_waitcnt vmcnt(0)
